# MLA attention unit prologue: first K/V/k_pe tile loads issued together with the Q fragment loads (one memory round trip instead of two)
# baseline (speedup 1.0000x reference)
.LBB0_478:
	s_and_b64 vcc, exec, s[10:11]
	s_cbranch_vccz .LBB0_444
	v_mov_b32_e32 v42, v240
	s_lshl_b32 s5, s5, 8
	v_readfirstlane_b32 s10, v42
	s_ashr_i32 s10, s10, 1
	s_andn2_b32 s10, s10, 31
	v_and_b32_e32 v28, 31, v42
	s_add_i32 s10, s10, s5
	v_or_b32_e32 v26, s10, v28
	v_add_u32_e32 v110, s59, v26
	v_ashrrev_i32_e32 v111, 31, v110
	v_lshlrev_b64 v[2:3], 10, v[110:111]
	v_bfe_u32 v43, v42, 5, 1
	s_mul_i32 s52, s58, 0x60
	v_lshl_add_u64 v[2:3], s[44:45], 0, v[2:3]
	v_lshl_add_u64 v[2:3], s[52:53], 1, v[2:3]
	v_lshlrev_b32_e32 v0, 4, v43
	v_lshl_add_u64 v[2:3], v[2:3], 0, v[0:1]
	global_load_dwordx4 v[22:25], v[2:3], off
	global_load_dwordx4 v[18:21], v[2:3], off offset:32
	global_load_dwordx4 v[14:17], v[2:3], off offset:64
	global_load_dwordx4 v[10:13], v[2:3], off offset:96
	global_load_dwordx4 v[6:9], v[2:3], off offset:128
	s_nop 0
	global_load_dwordx4 v[2:5], v[2:3], off offset:160
	v_ashrrev_i32_e32 v160, 3, v42
	v_add_u32_e32 v164, s59, v160
	v_ashrrev_i32_e32 v165, 31, v164
	v_lshlrev_b64 v[164:165], 10, v[164:165]
	v_mov_b32_e32 v162, s58
	v_lshlrev_b32_e32 v162, 8, v162
	v_mov_b32_e32 v163, v1
	v_lshl_add_u64 v[162:163], s[56:57], 0, v[162:163]
	v_lshl_add_u64 v[164:165], v[162:163], 0, v[164:165]
	v_lshlrev_b32_e32 v166, 3, v42
	v_and_b32_e32 v166, 56, v166
	v_lshlrev_b32_e32 v166, 1, v166
	v_mov_b32_e32 v167, v1
	v_lshl_add_u64 v[164:165], v[164:165], 0, v[166:167]
	global_load_dwordx4 v[148:151], v[164:165], off
	global_load_dwordx4 v[152:155], v[164:165], off offset:128
	v_bfe_u32 v160, v42, 2, 6
	v_or_b32_e32 v164, s59, v160
	v_ashrrev_i32_e32 v165, 31, v164
	v_lshlrev_b64 v[164:165], 6, v[164:165]
	v_lshl_add_u64 v[164:165], s[46:47], 0, v[164:165]
	v_and_b32_e32 v166, 3, v42
	v_lshlrev_b32_e32 v166, 4, v166
	v_lshl_add_u64 v[164:165], v[164:165], 0, v[166:167]
	global_load_dwordx4 v[156:159], v[164:165], off
	v_and_b32_e32 v29, 63, v42
	s_mov_b32 s5, 4
	s_mov_b32 s16, 2
	s_andn2_b64 vcc, exec, s[30:31]
	v_cmp_gt_u32_e64 s[36:37], 32, v29
	s_cbranch_vccnz .LBB0_481
	s_ashr_i32 s5, s10, 6
	v_cvt_f32_i32_e32 v0, s5
	v_and_b32_e32 v26, 63, v26
	v_and_b32_e32 v30, 64, v241
	v_cvt_f32_ubyte0_e32 v36, v26
	v_xor_b32_e32 v26, 32, v241
	v_add_u32_e32 v30, 64, v30
	v_cmp_lt_i32_e32 vcc, v26, v30
	v_cndmask_b32_e64 v27, 1.0, -1.0, s[36:37]
	s_mov_b32 s5, 32
	v_cndmask_b32_e32 v26, v241, v26, vcc
	v_lshlrev_b32_e32 v37, 2, v26
	v_mul_f32_e32 v26, 0.15915494, v0
	v_rndne_f32_e32 v26, v26
	v_fmamk_f32 v30, v26, 0xc0c90fdb, v0
	v_fmac_f32_e32 v30, 0x343bbd2e, v26
	v_mul_f32_e32 v26, 0.15915494, v30
	v_mul_f32_e32 v30, 0x3ea1e89b, v0
	v_mul_f32_e32 v32, 0.15915494, v30
	s_waitcnt vmcnt(0)
	ds_bpermute_b32 v31, v37, v6
	v_rndne_f32_e32 v32, v32
	v_fmac_f32_e32 v30, 0xc0c90fdb, v32
	v_sin_f32_e32 v34, v26
	v_cos_f32_e32 v26, v26
	v_fmac_f32_e32 v30, 0x343bbd2e, v32
	v_mul_f32_e32 v30, 0.15915494, v30
	v_sin_f32_e32 v38, v30
	v_cos_f32_e32 v30, v30
	s_waitcnt lgkmcnt(0)
	v_lshlrev_b32_e32 v33, 16, v31
	v_lshlrev_b32_e32 v32, 16, v6
	v_pk_mul_f32 v[32:33], v[26:27], v[32:33]
	v_and_b32_e32 v35, 0xffff0000, v31
	v_fmac_f32_e32 v32, v34, v33
	v_and_b32_e32 v34, 0xffff0000, v6
	v_mov_b32_e32 v31, v27
	v_pk_mul_f32 v[30:31], v[30:31], v[34:35]
	v_mul_f32_e32 v26, 0x3dcccccd, v0
	v_fmac_f32_e32 v30, v38, v31
	v_cvt_pk_bf16_f32 v6, v32, v30
	v_mul_f32_e32 v30, 0.15915494, v26
	v_rndne_f32_e32 v30, v30
	v_fmac_f32_e32 v26, 0xc0c90fdb, v30
	v_fmac_f32_e32 v26, 0x343bbd2e, v30
	v_mul_f32_e32 v30, 0x3d0186e3, v0
	v_mul_f32_e32 v32, 0.15915494, v30
	ds_bpermute_b32 v31, v37, v7
	v_rndne_f32_e32 v32, v32
	v_mul_f32_e32 v26, 0.15915494, v26
	v_fmac_f32_e32 v30, 0xc0c90fdb, v32
	v_sin_f32_e32 v34, v26
	v_cos_f32_e32 v26, v26
	v_fmac_f32_e32 v30, 0x343bbd2e, v32
	v_mul_f32_e32 v30, 0.15915494, v30
	v_sin_f32_e32 v38, v30
	v_cos_f32_e32 v30, v30
	s_waitcnt lgkmcnt(0)
	v_lshlrev_b32_e32 v33, 16, v31
	v_lshlrev_b32_e32 v32, 16, v7
	v_pk_mul_f32 v[32:33], v[26:27], v[32:33]
	v_and_b32_e32 v35, 0xffff0000, v31
	v_fmac_f32_e32 v32, v34, v33
	v_and_b32_e32 v34, 0xffff0000, v7
	v_mov_b32_e32 v31, v27
	v_pk_mul_f32 v[30:31], v[30:31], v[34:35]
	v_mul_f32_e32 v26, 0x3c23d70b, v0
	v_fmac_f32_e32 v30, v38, v31
	v_cvt_pk_bf16_f32 v7, v32, v30
	v_mul_f32_e32 v30, 0.15915494, v26
	v_rndne_f32_e32 v30, v30
	v_fmac_f32_e32 v26, 0xc0c90fdb, v30
	v_fmac_f32_e32 v26, 0x343bbd2e, v30
	v_mul_f32_e32 v30, 0x3b4f3e39, v0
	v_mul_f32_e32 v32, 0.15915494, v30
	ds_bpermute_b32 v31, v37, v8
	v_rndne_f32_e32 v32, v32
	v_mul_f32_e32 v26, 0.15915494, v26
	v_fmac_f32_e32 v30, 0xc0c90fdb, v32
	v_sin_f32_e32 v34, v26
	v_cos_f32_e32 v26, v26
	v_fmac_f32_e32 v30, 0x343bbd2e, v32
	v_mul_f32_e32 v30, 0.15915494, v30
	v_sin_f32_e32 v38, v30
	v_cos_f32_e32 v30, v30
	s_waitcnt lgkmcnt(0)
	v_lshlrev_b32_e32 v33, 16, v31
	v_lshlrev_b32_e32 v32, 16, v8
	v_pk_mul_f32 v[32:33], v[26:27], v[32:33]
	v_and_b32_e32 v35, 0xffff0000, v31
	v_fmac_f32_e32 v32, v34, v33
	v_and_b32_e32 v34, 0xffff0000, v8
	v_mov_b32_e32 v31, v27
	v_pk_mul_f32 v[30:31], v[30:31], v[34:35]
	v_mul_f32_e32 v26, 0x3a831270, v0
	v_fmac_f32_e32 v30, v38, v31
	v_cvt_pk_bf16_f32 v8, v32, v30
	v_mul_f32_e32 v30, 0.15915494, v26
	v_rndne_f32_e32 v30, v30
	v_fmac_f32_e32 v26, 0xc0c90fdb, v30
	v_mul_f32_e32 v0, 0x39a5cb61, v0
	v_fmac_f32_e32 v26, 0x343bbd2e, v30
	v_mul_f32_e32 v30, 0.15915494, v0
	ds_bpermute_b32 v31, v37, v9
	v_rndne_f32_e32 v30, v30
	v_mul_f32_e32 v26, 0.15915494, v26
	v_fmac_f32_e32 v0, 0xc0c90fdb, v30
	v_sin_f32_e32 v34, v26
	v_cos_f32_e32 v26, v26
	v_fmac_f32_e32 v0, 0x343bbd2e, v30
	v_mul_f32_e32 v0, 0.15915494, v0
	v_cos_f32_e32 v30, v0
	v_sin_f32_e32 v38, v0
	s_waitcnt lgkmcnt(0)
	v_lshlrev_b32_e32 v33, 16, v31
	v_lshlrev_b32_e32 v32, 16, v9
	v_pk_mul_f32 v[32:33], v[26:27], v[32:33]
	v_and_b32_e32 v35, 0xffff0000, v31
	v_fmac_f32_e32 v32, v34, v33
	v_and_b32_e32 v34, 0xffff0000, v9
	v_mov_b32_e32 v31, v27
	v_pk_mul_f32 v[30:31], v[30:31], v[34:35]
	v_mul_f32_e32 v26, 0.15915494, v36
	v_fmac_f32_e32 v30, v38, v31
	v_rndne_f32_e32 v26, v26
	v_cvt_pk_bf16_f32 v9, v32, v30
	v_fmamk_f32 v30, v26, 0xc0c90fdb, v36
	v_fmac_f32_e32 v30, 0x343bbd2e, v26
	v_mul_f32_e32 v26, 0.15915494, v30
	v_mul_f32_e32 v30, 0x3ea1e89b, v36
	v_mul_f32_e32 v32, 0.15915494, v30
	ds_bpermute_b32 v0, v37, v2
	v_rndne_f32_e32 v32, v32
	v_fmac_f32_e32 v30, 0xc0c90fdb, v32
	v_sin_f32_e32 v31, v26
	v_cos_f32_e32 v26, v26
	v_fmac_f32_e32 v30, 0x343bbd2e, v32
	v_mul_f32_e32 v30, 0.15915494, v30
	v_sin_f32_e32 v38, v30
	v_cos_f32_e32 v30, v30
	s_waitcnt lgkmcnt(0)
	v_lshlrev_b32_e32 v33, 16, v0
	v_lshlrev_b32_e32 v32, 16, v2
	v_pk_mul_f32 v[32:33], v[26:27], v[32:33]
	v_and_b32_e32 v35, 0xffff0000, v0
	v_fmac_f32_e32 v32, v31, v33
	v_and_b32_e32 v34, 0xffff0000, v2
	v_mov_b32_e32 v31, v27
	v_pk_mul_f32 v[30:31], v[30:31], v[34:35]
	v_mul_f32_e32 v26, 0x3dcccccd, v36
	v_fmac_f32_e32 v30, v38, v31
	v_cvt_pk_bf16_f32 v2, v32, v30
	v_mul_f32_e32 v30, 0.15915494, v26
	v_rndne_f32_e32 v30, v30
	v_fmac_f32_e32 v26, 0xc0c90fdb, v30
	v_fmac_f32_e32 v26, 0x343bbd2e, v30
	v_mul_f32_e32 v30, 0x3d0186e3, v36
	v_mul_f32_e32 v32, 0.15915494, v30
	ds_bpermute_b32 v0, v37, v3
	v_rndne_f32_e32 v32, v32
	v_mul_f32_e32 v26, 0.15915494, v26
	v_fmac_f32_e32 v30, 0xc0c90fdb, v32
	v_sin_f32_e32 v31, v26
	v_cos_f32_e32 v26, v26
	v_fmac_f32_e32 v30, 0x343bbd2e, v32
	v_mul_f32_e32 v30, 0.15915494, v30
	v_sin_f32_e32 v38, v30
	v_cos_f32_e32 v30, v30
	s_waitcnt lgkmcnt(0)
	v_lshlrev_b32_e32 v33, 16, v0
	v_lshlrev_b32_e32 v32, 16, v3
	v_pk_mul_f32 v[32:33], v[26:27], v[32:33]
	v_and_b32_e32 v35, 0xffff0000, v0
	v_fmac_f32_e32 v32, v31, v33
	v_and_b32_e32 v34, 0xffff0000, v3
	v_mov_b32_e32 v31, v27
	v_pk_mul_f32 v[30:31], v[30:31], v[34:35]
	v_mul_f32_e32 v26, 0x3c23d70b, v36
	v_fmac_f32_e32 v30, v38, v31
	v_cvt_pk_bf16_f32 v3, v32, v30
	v_mul_f32_e32 v30, 0.15915494, v26
	v_rndne_f32_e32 v30, v30
	v_fmac_f32_e32 v26, 0xc0c90fdb, v30
	v_fmac_f32_e32 v26, 0x343bbd2e, v30
	v_mul_f32_e32 v30, 0x3b4f3e39, v36
	v_mul_f32_e32 v32, 0.15915494, v30
	ds_bpermute_b32 v0, v37, v4
	v_rndne_f32_e32 v32, v32
	v_mul_f32_e32 v26, 0.15915494, v26
	v_fmac_f32_e32 v30, 0xc0c90fdb, v32
	v_sin_f32_e32 v31, v26
	v_cos_f32_e32 v26, v26
	v_fmac_f32_e32 v30, 0x343bbd2e, v32
	v_mul_f32_e32 v30, 0.15915494, v30
	v_sin_f32_e32 v38, v30
	v_cos_f32_e32 v30, v30
	s_waitcnt lgkmcnt(0)
	v_lshlrev_b32_e32 v33, 16, v0
	v_lshlrev_b32_e32 v32, 16, v4
	v_pk_mul_f32 v[32:33], v[26:27], v[32:33]
	v_and_b32_e32 v35, 0xffff0000, v0
	v_fmac_f32_e32 v32, v31, v33
	v_and_b32_e32 v34, 0xffff0000, v4
	v_mov_b32_e32 v31, v27
	v_pk_mul_f32 v[30:31], v[30:31], v[34:35]
	v_mul_f32_e32 v26, 0x3a831270, v36
	v_fmac_f32_e32 v30, v38, v31
	v_cvt_pk_bf16_f32 v4, v32, v30
	v_mul_f32_e32 v30, 0.15915494, v26
	v_rndne_f32_e32 v30, v30
	v_fmac_f32_e32 v26, 0xc0c90fdb, v30
	v_fmac_f32_e32 v26, 0x343bbd2e, v30
	v_mul_f32_e32 v30, 0x39a5cb61, v36
	v_mul_f32_e32 v32, 0.15915494, v30
	ds_bpermute_b32 v0, v37, v5
	v_rndne_f32_e32 v32, v32
	v_mul_f32_e32 v26, 0.15915494, v26
	v_fmac_f32_e32 v30, 0xc0c90fdb, v32
	v_sin_f32_e32 v31, v26
	v_cos_f32_e32 v26, v26
	v_fmac_f32_e32 v30, 0x343bbd2e, v32
	v_mul_f32_e32 v30, 0.15915494, v30
	v_sin_f32_e32 v36, v30
	v_cos_f32_e32 v30, v30
	s_waitcnt lgkmcnt(0)
	v_lshlrev_b32_e32 v33, 16, v0
	v_lshlrev_b32_e32 v32, 16, v5
	v_pk_mul_f32 v[32:33], v[26:27], v[32:33]
	v_and_b32_e32 v35, 0xffff0000, v0
	v_fmac_f32_e32 v32, v31, v33
	v_and_b32_e32 v34, 0xffff0000, v5
	v_mov_b32_e32 v31, v27
	v_pk_mul_f32 v[26:27], v[30:31], v[34:35]
	s_mov_b32 s16, 38
	v_fmac_f32_e32 v26, v36, v27
	v_cvt_pk_bf16_f32 v5, v32, v26
.LBB0_481:
	s_waitcnt vmcnt(0)
	v_lshlrev_b32_e32 v0, 16, v22
	v_mul_f32_e32 v0, 0x3e16c740, v0
	v_and_b32_e32 v22, 0xffff0000, v22
	v_mul_f32_e32 v22, 0x3e16c740, v22
	v_cvt_pk_bf16_f32 v74, v0, v22
	v_lshlrev_b32_e32 v0, 16, v23
	v_mul_f32_e32 v0, 0x3e16c740, v0
	v_and_b32_e32 v22, 0xffff0000, v23
	v_mul_f32_e32 v22, 0x3e16c740, v22
	v_cvt_pk_bf16_f32 v75, v0, v22
	v_lshlrev_b32_e32 v0, 16, v24
	v_mul_f32_e32 v0, 0x3e16c740, v0
	v_and_b32_e32 v22, 0xffff0000, v24
	v_mul_f32_e32 v22, 0x3e16c740, v22
	v_cvt_pk_bf16_f32 v76, v0, v22
	v_lshlrev_b32_e32 v0, 16, v25
	v_mul_f32_e32 v0, 0x3e16c740, v0
	v_and_b32_e32 v22, 0xffff0000, v25
	v_mul_f32_e32 v22, 0x3e16c740, v22
	v_cvt_pk_bf16_f32 v77, v0, v22
	v_lshlrev_b32_e32 v0, 16, v18
	v_mul_f32_e32 v0, 0x3e16c740, v0
	v_and_b32_e32 v18, 0xffff0000, v18
	v_mul_f32_e32 v18, 0x3e16c740, v18
	v_cvt_pk_bf16_f32 v66, v0, v18
	v_lshlrev_b32_e32 v0, 16, v19
	v_mul_f32_e32 v0, 0x3e16c740, v0
	v_and_b32_e32 v18, 0xffff0000, v19
	v_mul_f32_e32 v18, 0x3e16c740, v18
	v_cvt_pk_bf16_f32 v67, v0, v18
	v_lshlrev_b32_e32 v0, 16, v20
	v_mul_f32_e32 v0, 0x3e16c740, v0
	v_and_b32_e32 v18, 0xffff0000, v20
	v_mul_f32_e32 v18, 0x3e16c740, v18
	v_cvt_pk_bf16_f32 v68, v0, v18
	v_lshlrev_b32_e32 v0, 16, v21
	v_mul_f32_e32 v0, 0x3e16c740, v0
	v_and_b32_e32 v18, 0xffff0000, v21
	v_mul_f32_e32 v18, 0x3e16c740, v18
	v_cvt_pk_bf16_f32 v69, v0, v18
	v_lshlrev_b32_e32 v0, 16, v14
	v_mul_f32_e32 v0, 0x3e16c740, v0
	v_and_b32_e32 v14, 0xffff0000, v14
	v_mul_f32_e32 v14, 0x3e16c740, v14
	v_cvt_pk_bf16_f32 v82, v0, v14
	v_lshlrev_b32_e32 v0, 16, v15
	v_mul_f32_e32 v0, 0x3e16c740, v0
	v_and_b32_e32 v14, 0xffff0000, v15
	v_mul_f32_e32 v14, 0x3e16c740, v14
	v_cvt_pk_bf16_f32 v83, v0, v14
	v_lshlrev_b32_e32 v0, 16, v16
	v_mul_f32_e32 v0, 0x3e16c740, v0
	v_and_b32_e32 v14, 0xffff0000, v16
	v_mul_f32_e32 v14, 0x3e16c740, v14
	v_cvt_pk_bf16_f32 v84, v0, v14
	v_lshlrev_b32_e32 v0, 16, v17
	v_mul_f32_e32 v0, 0x3e16c740, v0
	v_and_b32_e32 v14, 0xffff0000, v17
	v_mul_f32_e32 v14, 0x3e16c740, v14
	v_cvt_pk_bf16_f32 v85, v0, v14
	v_lshlrev_b32_e32 v0, 16, v10
	v_mul_f32_e32 v0, 0x3e16c740, v0
	v_and_b32_e32 v10, 0xffff0000, v10
	v_mul_f32_e32 v10, 0x3e16c740, v10
	v_cvt_pk_bf16_f32 v70, v0, v10
	v_lshlrev_b32_e32 v0, 16, v11
	v_mul_f32_e32 v0, 0x3e16c740, v0
	v_and_b32_e32 v10, 0xffff0000, v11
	v_mul_f32_e32 v10, 0x3e16c740, v10
	v_cvt_pk_bf16_f32 v71, v0, v10
	v_lshlrev_b32_e32 v0, 16, v12
	v_mul_f32_e32 v0, 0x3e16c740, v0
	v_and_b32_e32 v10, 0xffff0000, v12
	v_mul_f32_e32 v10, 0x3e16c740, v10
	v_cvt_pk_bf16_f32 v72, v0, v10
	v_lshlrev_b32_e32 v0, 16, v13
	v_mul_f32_e32 v0, 0x3e16c740, v0
	v_and_b32_e32 v10, 0xffff0000, v13
	v_mul_f32_e32 v10, 0x3e16c740, v10
	v_cvt_pk_bf16_f32 v73, v0, v10
	v_lshlrev_b32_e32 v0, 16, v6
	v_mul_f32_e32 v0, 0x3e16c740, v0
	v_and_b32_e32 v6, 0xffff0000, v6
	v_mul_f32_e32 v6, 0x3e16c740, v6
	v_cvt_pk_bf16_f32 v86, v0, v6
	v_lshlrev_b32_e32 v0, 16, v7
	v_mul_f32_e32 v0, 0x3e16c740, v0
	v_and_b32_e32 v6, 0xffff0000, v7
	v_mul_f32_e32 v6, 0x3e16c740, v6
	v_cvt_pk_bf16_f32 v87, v0, v6
	v_lshlrev_b32_e32 v0, 16, v8
	v_mul_f32_e32 v0, 0x3e16c740, v0
	v_and_b32_e32 v6, 0xffff0000, v8
	v_mul_f32_e32 v6, 0x3e16c740, v6
	v_cvt_pk_bf16_f32 v88, v0, v6
	v_lshlrev_b32_e32 v0, 16, v9
	v_mul_f32_e32 v0, 0x3e16c740, v0
	v_and_b32_e32 v6, 0xffff0000, v9
	v_mul_f32_e32 v6, 0x3e16c740, v6
	v_cvt_pk_bf16_f32 v89, v0, v6
	v_lshlrev_b32_e32 v0, 16, v2
	v_and_b32_e32 v2, 0xffff0000, v2
	v_mul_f32_e32 v2, 0x3e16c740, v2
	v_mul_f32_e32 v0, 0x3e16c740, v0
	v_cvt_pk_bf16_f32 v78, v0, v2
	v_and_b32_e32 v2, 0xffff0000, v3
	v_lshlrev_b32_e32 v0, 16, v3
	v_mul_f32_e32 v2, 0x3e16c740, v2
	v_mul_f32_e32 v0, 0x3e16c740, v0
	v_cvt_pk_bf16_f32 v79, v0, v2
	v_and_b32_e32 v2, 0xffff0000, v4
	v_lshlrev_b32_e32 v0, 16, v4
	v_mul_f32_e32 v2, 0x3e16c740, v2
	v_mul_f32_e32 v0, 0x3e16c740, v0
	v_cvt_pk_bf16_f32 v80, v0, v2
	v_and_b32_e32 v2, 0xffff0000, v5
	v_lshlrev_b32_e32 v0, 16, v5
	v_mul_f32_e32 v2, 0x3e16c740, v2
	v_ashrrev_i32_e32 v44, 3, v42
	v_mul_f32_e32 v0, 0x3e16c740, v0
	v_cvt_pk_bf16_f32 v81, v0, v2
	s_lshl_b32 s10, s58, 8
	v_add_u32_e32 v2, s59, v44
	s_add_u32 s10, s56, s10
	v_ashrrev_i32_e32 v3, 31, v2
	v_lshlrev_b32_e32 v0, 3, v42
	s_addc_u32 s11, s57, 0
	v_lshlrev_b64 v[2:3], 10, v[2:3]
	v_and_b32_e32 v10, 56, v0
	v_lshl_add_u64 v[2:3], s[10:11], 0, v[2:3]
	v_lshlrev_b32_e32 v0, 1, v10
	v_lshl_add_u64 v[2:3], v[2:3], 0, v[0:1]
	s_nop 0
	s_movk_i32 s14, 0xff
	v_and_b32_e32 v11, 3, v42
	v_cmp_lt_i32_e32 vcc, s14, v42
	s_movk_i32 s14, 0x100
	v_bfe_u32 v45, v42, 2, 6
	v_cmp_gt_i32_e64 s[38:39], s14, v42
	v_mov_b32_e32 v94, v1
	v_mov_b32_e32 v95, v1
	v_mov_b32_e32 v96, v1
	v_mov_b32_e32 v97, v1
	v_lshlrev_b32_e32 v112, 4, v11
	s_and_saveexec_b64 s[14:15], s[38:39]
	s_cbranch_execz .LBB0_483
	v_or_b32_e32 v12, s59, v45
	v_ashrrev_i32_e32 v13, 31, v12
	v_lshlrev_b64 v[12:13], 6, v[12:13]
	v_lshl_add_u64 v[12:13], s[46:47], 0, v[12:13]
	v_mov_b32_e32 v113, v1
	v_lshl_add_u64 v[12:13], v[12:13], 0, v[112:113]

.LBB0_485:
	s_or_b64 exec, exec, s[14:15]
	s_movk_i32 s14, 0x68
	v_mad_u64_u32 v[12:13], s[14:15], v44, s14, v[10:11]
	v_lshlrev_b32_e32 v120, 1, v12
	v_add_u32_e32 v46, 0, v120
	s_barrier
	s_waitcnt vmcnt(1)
	ds_write_b128 v46, v[148:151]
	v_lshlrev_b32_e32 v6, 3, v44
	v_sub_u32_e32 v6, v12, v6
	v_lshlrev_b32_e32 v121, 1, v6
	v_add_u32_e32 v47, 0, v121
	v_mul_u32_u24_e32 v122, 0xd0, v45
	s_waitcnt vmcnt(0)
	ds_write_b128 v47, v[152:155] offset:13312
	s_and_saveexec_b64 s[14:15], vcc
	s_xor_b64 s[14:15], exec, s[14:15]
	v_mul_u32_u24_e32 v122, 0xd0, v45
	s_andn2_saveexec_b64 s[14:15], s[14:15]
	v_add3_u32 v2, 0, v112, v122
	ds_write_b128 v2, v[156:159] offset:128
	s_or_b64 exec, exec, s[14:15]
	s_or_b32 s14, s59, 64
	v_add_u32_e32 v2, s14, v44
	v_ashrrev_i32_e32 v3, 31, v2
	v_lshl_add_u64 v[114:115], s[10:11], 0, v[0:1]
	v_lshlrev_b64 v[2:3], 10, v[2:3]
	v_lshl_add_u64 v[2:3], v[114:115], 0, v[2:3]
	s_waitcnt lgkmcnt(0)
	s_barrier
	global_load_dwordx4 v[34:37], v[2:3], off
	global_load_dwordx4 v[38:41], v[2:3], off offset:128
	v_mov_b32_e32 v113, v1
	v_lshl_add_u64 v[116:117], s[46:47], 0, v[112:113]
	s_and_saveexec_b64 s[10:11], s[38:39]
	s_cbranch_execz .LBB0_491
	v_or_b32_e32 v2, s14, v45
	v_ashrrev_i32_e32 v3, 31, v2
	v_lshlrev_b64 v[2:3], 6, v[2:3]
	v_lshl_add_u64 v[2:3], v[116:117], 0, v[2:3]
	global_load_dwordx4 v[94:97], v[2:3], off
